# gla_s3: next chunk's A/v fragments L2-prefetched with dummy loads one chunk ahead; counted waits adjusted
# baseline (speedup 1.0000x reference)
.LBB0_739:
	s_ashr_i32 s11, s10, 31
	s_lshl_b64 s[4:5], s[10:11], 13
	v_lshl_add_u64 v[64:65], v[212:213], 0, s[4:5]
	s_lshl_b64 s[4:5], s[10:11], 16
	v_lshl_add_u64 v[66:67], v[216:217], 0, s[4:5]
	global_load_dwordx4 v[144:147], v[64:65], off
	global_load_dwordx4 v[148:151], v[64:65], off offset:32
	global_load_dwordx4 v[140:143], v[66:67], off
	global_load_dwordx4 v[136:139], v[66:67], off offset:1024
	global_load_dwordx4 v[152:155], v[64:65], off offset:64
	global_load_dwordx4 v[156:159], v[64:65], off offset:96
	global_load_dwordx4 v[132:135], v[66:67], off offset:2048
	global_load_dwordx4 v[128:131], v[66:67], off offset:3072
	s_cmp_lg_u32 s12, 0x1c0000
	s_cselect_b64 s[14:15], -1, 0
	s_cmp_eq_u32 s12, 0x1c0000
	s_cbranch_scc1 .LBB0_741
	s_add_i32 s4, s10, 4
	s_ashr_i32 s5, s4, 31
	s_lshl_b64 s[4:5], s[4:5], 15
	v_lshl_add_u64 v[64:65], v[170:171], 0, s[4:5]
	v_add_co_u32_e32 v66, vcc, 0x2000, v64
	s_nop 1
	v_addc_co_u32_e32 v67, vcc, 0, v65, vcc
	global_load_dwordx4 v[96:99], v[64:65], off
	global_load_dwordx4 v[104:107], v[66:67], off
	v_add_co_u32_e32 v66, vcc, 0x4000, v64
	s_nop 1
	v_addc_co_u32_e32 v67, vcc, 0, v65, vcc
	v_add_co_u32_e32 v64, vcc, 0x6000, v64
	s_nop 1
	v_addc_co_u32_e32 v65, vcc, 0, v65, vcc
	global_load_dwordx4 v[112:115], v[66:67], off
	global_load_dwordx4 v[120:123], v[64:65], off
	s_add_i32 s4, s10, 4
	s_ashr_i32 s5, s4, 31
	s_lshl_b64 s[16:17], s[4:5], 13
	v_lshl_add_u64 v[248:249], v[212:213], 0, s[16:17]
	s_lshl_b64 s[16:17], s[4:5], 16
	v_lshl_add_u64 v[250:251], v[216:217], 0, s[16:17]
	global_load_dwordx4 v[244:247], v[248:249], off
	global_load_dwordx4 v[244:247], v[248:249], off offset:32
	global_load_dwordx4 v[244:247], v[250:251], off
	global_load_dwordx4 v[244:247], v[250:251], off offset:1024
	global_load_dwordx4 v[244:247], v[248:249], off offset:64
	global_load_dwordx4 v[244:247], v[248:249], off offset:96
	global_load_dwordx4 v[244:247], v[250:251], off offset:2048
	global_load_dwordx4 v[244:247], v[250:251], off offset:3072

.LBB0_747:
	v_cndmask_b32_e64 v64, v80, v64, s[6:7]
	v_cndmask_b32_e64 v65, v81, v65, s[6:7]
	v_cndmask_b32_e64 v66, v82, v66, s[6:7]
	v_cndmask_b32_e64 v67, v83, v67, s[6:7]
	v_cndmask_b32_e64 v68, v84, v68, s[6:7]
	v_cndmask_b32_e64 v69, v85, v69, s[6:7]
	v_cndmask_b32_e64 v70, v86, v70, s[6:7]
	v_cndmask_b32_e64 v71, v87, v71, s[6:7]
	v_cndmask_b32_e64 v72, v88, v72, s[6:7]
	v_cndmask_b32_e64 v73, v89, v73, s[6:7]
	v_cndmask_b32_e64 v74, v90, v74, s[6:7]
	v_cndmask_b32_e64 v75, v91, v75, s[6:7]
	v_cndmask_b32_e64 v76, v92, v76, s[6:7]
	v_cndmask_b32_e64 v77, v93, v77, s[6:7]
	v_cndmask_b32_e64 v78, v94, v78, s[6:7]
	v_cndmask_b32_e64 v79, v95, v79, s[6:7]
	s_waitcnt lgkmcnt(0)
	v_add_f32_e32 v64, v64, v234
	v_add_f32_e32 v65, v65, v235
	v_add_f32_e32 v66, v66, v232
	v_add_f32_e32 v67, v67, v233
	v_add_f32_e32 v68, v68, v230
	v_add_f32_e32 v69, v69, v231
	v_add_f32_e32 v70, v70, v228
	v_add_f32_e32 v71, v71, v229
	v_add_f32_e32 v72, v72, v226
	v_add_f32_e32 v73, v73, v227
	v_add_f32_e32 v74, v74, v224
	v_add_f32_e32 v75, v75, v225
	v_add_f32_e32 v76, v76, v222
	v_add_f32_e32 v77, v77, v223
	v_add_f32_e32 v78, v78, v220
	v_add_f32_e32 v79, v79, v221
	s_mov_b32 s14, 0x2ec00000
	v_add_u32_e32 v92, s21, v210
	s_waitcnt vmcnt(16)
	v_mfma_f32_32x32x16_bf16 v[64:79], v[144:147], v[140:143], v[64:79]
	v_mfma_f32_32x32x16_bf16 v[64:79], v[148:151], v[136:139], v[64:79]
	v_mfma_f32_32x32x16_bf16 v[64:79], v[152:155], v[132:135], v[64:79]
	v_mfma_f32_32x32x16_bf16 v[64:79], v[156:159], v[128:131], v[64:79]
	s_nop 11
	v_bfe_u32 v80, v64, 16, 1
	v_add3_u32 v64, v64, v80, s49
	v_lshl_add_u64 v[80:81], v[218:219], 0, s[12:13]
	v_add_co_u32_e32 v82, vcc, s14, v80
	s_mov_b32 s14, 0x2ec01000
	s_nop 0
	v_addc_co_u32_e32 v83, vcc, 0, v81, vcc
	global_store_short_d16_hi v[82:83], v64, off
	v_bfe_u32 v64, v65, 16, 1
	v_add3_u32 v82, v65, v64, s49
	v_add_co_u32_e32 v64, vcc, s14, v80
	s_mov_b32 s14, 0x2ec02000
	s_nop 0
	v_addc_co_u32_e32 v65, vcc, 0, v81, vcc
	global_store_short_d16_hi v[64:65], v82, off
	v_bfe_u32 v64, v66, 16, 1
	v_add3_u32 v66, v66, v64, s49
	v_add_co_u32_e32 v64, vcc, s14, v80
	s_mov_b32 s14, 0x2ec03000
	s_nop 0
	v_addc_co_u32_e32 v65, vcc, 0, v81, vcc
	global_store_short_d16_hi v[64:65], v66, off
	v_bfe_u32 v64, v67, 16, 1
	v_add3_u32 v66, v67, v64, s49
	v_add_co_u32_e32 v64, vcc, s14, v80
	s_mov_b32 s14, 0x2ec08000
	s_nop 0
	v_addc_co_u32_e32 v65, vcc, 0, v81, vcc
	global_store_short_d16_hi v[64:65], v66, off
	v_bfe_u32 v64, v68, 16, 1
	v_add3_u32 v66, v68, v64, s49
	v_add_co_u32_e32 v64, vcc, s14, v80
	s_mov_b32 s14, 0x2ec09000
	s_nop 0
	v_addc_co_u32_e32 v65, vcc, 0, v81, vcc
	global_store_short_d16_hi v[64:65], v66, off
	v_bfe_u32 v64, v69, 16, 1
	v_add3_u32 v66, v69, v64, s49
	v_add_co_u32_e32 v64, vcc, s14, v80
	s_mov_b32 s14, 0x2ec0a000
	s_nop 0
	v_addc_co_u32_e32 v65, vcc, 0, v81, vcc
	global_store_short_d16_hi v[64:65], v66, off
	v_bfe_u32 v64, v70, 16, 1
	v_add3_u32 v66, v70, v64, s49
	v_add_co_u32_e32 v64, vcc, s14, v80
	s_mov_b32 s14, 0x2ec0b000
	s_nop 0
	v_addc_co_u32_e32 v65, vcc, 0, v81, vcc
	global_store_short_d16_hi v[64:65], v66, off
	v_bfe_u32 v64, v71, 16, 1
	v_add3_u32 v66, v71, v64, s49
	v_add_co_u32_e32 v64, vcc, s14, v80
	s_mov_b32 s14, 0x2ec10000
	s_nop 0
	v_addc_co_u32_e32 v65, vcc, 0, v81, vcc
	global_store_short_d16_hi v[64:65], v66, off
	v_bfe_u32 v64, v72, 16, 1
	v_add3_u32 v66, v72, v64, s49
	v_add_co_u32_e32 v64, vcc, s14, v80
	s_mov_b32 s14, 0x2ec11000
	s_nop 0
	v_addc_co_u32_e32 v65, vcc, 0, v81, vcc
	global_store_short_d16_hi v[64:65], v66, off
	v_bfe_u32 v64, v73, 16, 1
	v_add3_u32 v66, v73, v64, s49
	v_add_co_u32_e32 v64, vcc, s14, v80
	s_mov_b32 s14, 0x2ec12000
	s_nop 0
	v_addc_co_u32_e32 v65, vcc, 0, v81, vcc
	global_store_short_d16_hi v[64:65], v66, off
	v_bfe_u32 v64, v74, 16, 1
	v_add3_u32 v66, v74, v64, s49
	v_add_co_u32_e32 v64, vcc, s14, v80
	s_mov_b32 s14, 0x2ec13000
	s_nop 0
	v_addc_co_u32_e32 v65, vcc, 0, v81, vcc
	global_store_short_d16_hi v[64:65], v66, off
	v_bfe_u32 v64, v75, 16, 1
	v_add3_u32 v66, v75, v64, s49
	v_add_co_u32_e32 v64, vcc, s14, v80
	s_mov_b32 s14, 0x2ec18000
	s_nop 0
	v_addc_co_u32_e32 v65, vcc, 0, v81, vcc
	global_store_short_d16_hi v[64:65], v66, off
	v_bfe_u32 v64, v76, 16, 1
	v_add3_u32 v66, v76, v64, s49
	v_add_co_u32_e32 v64, vcc, s14, v80
	s_mov_b32 s14, 0x2ec19000
	s_nop 0
	v_addc_co_u32_e32 v65, vcc, 0, v81, vcc
	global_store_short_d16_hi v[64:65], v66, off
	v_bfe_u32 v64, v77, 16, 1
	v_add3_u32 v66, v77, v64, s49
	v_add_co_u32_e32 v64, vcc, s14, v80
	s_mov_b32 s14, 0x2ec1a000
	s_nop 0
	v_addc_co_u32_e32 v65, vcc, 0, v81, vcc
	global_store_short_d16_hi v[64:65], v66, off
	v_bfe_u32 v64, v78, 16, 1
	v_add3_u32 v66, v78, v64, s49
	v_add_co_u32_e32 v64, vcc, s14, v80
	s_mov_b32 s14, 0x2ec1b000
	s_nop 0
	v_addc_co_u32_e32 v65, vcc, 0, v81, vcc
	global_store_short_d16_hi v[64:65], v66, off
	v_bfe_u32 v64, v79, 16, 1
	v_add3_u32 v66, v79, v64, s49
	v_add_co_u32_e32 v64, vcc, s14, v80
	s_nop 1
	v_addc_co_u32_e32 v65, vcc, 0, v81, vcc
	global_store_short_d16_hi v[64:65], v66, off
	ds_read_b128 v[64:67], v92 offset:96
	ds_read_b128 v[68:71], v92 offset:64
	ds_read_b128 v[72:75], v92 offset:32
	ds_read_b128 v[76:79], v92
	s_and_b64 vcc, exec, s[4:5]
	s_waitcnt lgkmcnt(0)
	v_pk_mul_f32 v[12:13], v[12:13], v[64:65]
	v_pk_mul_f32 v[8:9], v[8:9], v[68:69]
	v_pk_mul_f32 v[14:15], v[14:15], v[66:67]
	v_pk_mul_f32 v[10:11], v[10:11], v[70:71]
	ds_read_b128 v[64:67], v92 offset:192
	ds_read_b128 v[68:71], v92 offset:224
	ds_read_b128 v[80:83], v92 offset:128
	ds_read_b128 v[84:87], v92 offset:160
	v_pk_mul_f32 v[4:5], v[4:5], v[72:73]
	v_pk_mul_f32 v[0:1], v[0:1], v[76:77]
	v_pk_mul_f32 v[6:7], v[6:7], v[74:75]
	v_pk_mul_f32 v[2:3], v[2:3], v[78:79]
	s_waitcnt lgkmcnt(0)
	v_pk_mul_f32 v[28:29], v[28:29], v[68:69]
	v_pk_mul_f32 v[24:25], v[24:25], v[64:65]
	v_pk_mul_f32 v[30:31], v[30:31], v[70:71]
	v_pk_mul_f32 v[26:27], v[26:27], v[66:67]
	ds_read_b128 v[64:67], v92 offset:320
	ds_read_b128 v[68:71], v92 offset:352
	ds_read_b128 v[72:75], v92 offset:256
	ds_read_b128 v[76:79], v92 offset:288
	ds_read_b128 v[88:91], v199
	v_pk_mul_f32 v[20:21], v[20:21], v[84:85]
	v_pk_mul_f32 v[16:17], v[16:17], v[80:81]
	v_pk_mul_f32 v[22:23], v[22:23], v[86:87]
	v_pk_mul_f32 v[18:19], v[18:19], v[82:83]
	ds_read_b128 v[80:83], v199 offset:4096
	ds_read_b128 v[84:87], v199 offset:1024
	s_waitcnt lgkmcnt(0)
	v_pk_mul_f32 v[44:45], v[44:45], v[68:69]
	v_pk_mul_f32 v[40:41], v[40:41], v[64:65]
	v_pk_mul_f32 v[36:37], v[36:37], v[76:77]
	v_pk_mul_f32 v[32:33], v[32:33], v[72:73]
	v_mfma_f32_32x32x16_bf16 v[0:15], v[88:91], v[140:143], v[0:15]
	v_mul_f32_e64 v46, v46, v70
	v_mul_f32_e64 v47, v47, v71
	v_mul_f32_e64 v42, v42, v66
	v_mul_f32_e64 v43, v43, v67
	v_mul_f32_e64 v38, v38, v78
	v_mul_f32_e64 v39, v39, v79
	ds_read_b128 v[64:67], v92 offset:448
	ds_read_b128 v[68:71], v92 offset:480
	ds_read_b128 v[76:79], v199 offset:8192
	ds_read_b128 v[88:91], v199 offset:5120
	v_pk_mul_f32 v[34:35], v[34:35], v[74:75]
	s_waitcnt lgkmcnt(0)
	v_pk_mul_f32 v[56:57], v[56:57], v[64:65]
	v_pk_mul_f32 v[60:61], v[60:61], v[68:69]
	v_mfma_f32_32x32x16_bf16 v[16:31], v[80:83], v[140:143], v[16:31]
	ds_read_b128 v[72:75], v92 offset:384
	ds_read_b128 v[80:83], v92 offset:416
	ds_read_b128 v[92:95], v199 offset:12288
	ds_read_b128 v[144:147], v199 offset:9216
	v_mul_f32_e64 v62, v62, v70
	v_mul_f32_e64 v63, v63, v71
	v_pk_mul_f32 v[58:59], v[58:59], v[66:67]
	s_waitcnt lgkmcnt(0)
	v_pk_mul_f32 v[48:49], v[48:49], v[72:73]
	v_pk_mul_f32 v[52:53], v[52:53], v[80:81]
	v_pk_mul_f32 v[54:55], v[54:55], v[82:83]
	v_pk_mul_f32 v[50:51], v[50:51], v[74:75]
	ds_read_b128 v[64:67], v199 offset:13312
	v_mfma_f32_32x32x16_bf16 v[32:47], v[76:79], v[140:143], v[32:47]
	v_mfma_f32_32x32x16_bf16 v[48:63], v[92:95], v[140:143], v[48:63]
	v_mfma_f32_32x32x16_bf16 v[0:15], v[84:87], v[136:139], v[0:15]
	v_mfma_f32_32x32x16_bf16 v[16:31], v[88:91], v[136:139], v[16:31]
	s_waitcnt lgkmcnt(0)
	v_mfma_f32_32x32x16_bf16 v[48:63], v[64:67], v[136:139], v[48:63]
	ds_read_b128 v[64:67], v199 offset:2048
	ds_read_b128 v[68:71], v199 offset:3072
	v_mfma_f32_32x32x16_bf16 v[32:47], v[144:147], v[136:139], v[32:47]
	s_waitcnt lgkmcnt(0)
	v_mfma_f32_32x32x16_bf16 v[0:15], v[64:67], v[132:135], v[0:15]
	ds_read_b128 v[64:67], v199 offset:6144
	ds_read_b128 v[72:75], v199 offset:7168
	s_waitcnt lgkmcnt(0)
	v_mfma_f32_32x32x16_bf16 v[16:31], v[64:67], v[132:135], v[16:31]
	ds_read_b128 v[64:67], v199 offset:10240
	ds_read_b128 v[76:79], v199 offset:11264
	s_waitcnt lgkmcnt(0)
	v_mfma_f32_32x32x16_bf16 v[32:47], v[64:67], v[132:135], v[32:47]
	ds_read_b128 v[64:67], v199 offset:14336
	ds_read_b128 v[80:83], v199 offset:15360
	s_waitcnt lgkmcnt(0)
	v_mfma_f32_32x32x16_bf16 v[48:63], v[64:67], v[132:135], v[48:63]
	v_mfma_f32_32x32x16_bf16 v[0:15], v[68:71], v[128:131], v[0:15]
	v_mfma_f32_32x32x16_bf16 v[16:31], v[72:75], v[128:131], v[16:31]
	v_mfma_f32_32x32x16_bf16 v[32:47], v[76:79], v[128:131], v[32:47]
	v_mfma_f32_32x32x16_bf16 v[48:63], v[80:83], v[128:131], v[48:63]
	s_cbranch_vccnz .LBB0_738
	s_xor_b32 s4, s11, 0x8000
	v_add_u32_e32 v64, s4, v177
	s_waitcnt vmcnt(28)
	ds_write_b128 v64, v[96:99]
	ds_write_b128 v64, v[104:107] offset:8192
	ds_write_b128 v64, v[112:115] offset:16384
	ds_write_b128 v64, v[120:123] offset:24576
	s_branch .LBB0_738
